# counted waits in the SSD scan loop: the three vmcnt(0) waits become vmcnt(2) so the two Y-store acknowledgements per chunk are not waited for; rest as clamp-folded version
# baseline (speedup 1.0000x reference)
.LBB0_1649:
	s_or_b64 exec, exec, s[30:31]
	s_add_i32 s1, s1, 0x80000
	s_add_i32 s4, s4, 0x80000
	s_waitcnt vmcnt(2)
	s_add_u32 s94, s94, 0x19800
	s_addc_u32 s95, s95, 0
	s_mov_b64 s[2:3], 0x4000
	v_add_u32_e32 v94, 0x80, v94
	v_lshl_add_u64 v[96:97], v[96:97], 0, s[2:3]
	s_cmp_eq_u32 s94, 0x330000
	s_waitcnt vmcnt(2)
	v_mov_b32_e32 v24, v112
	v_mov_b32_e32 v25, v113
	v_mov_b32_e32 v26, v110
	v_mov_b32_e32 v27, v111
	v_mov_b32_e32 v20, v108
	v_mov_b32_e32 v21, v109
	v_mov_b32_e32 v22, v106
	v_mov_b32_e32 v23, v107
	v_mov_b32_e32 v16, v104
	v_mov_b32_e32 v17, v105
	v_mov_b32_e32 v18, v102
	v_mov_b32_e32 v19, v103
	v_mov_b32_e32 v12, v100
	v_mov_b32_e32 v13, v101
	v_mov_b32_e32 v14, v98
	v_mov_b32_e32 v15, v99
	s_waitcnt lgkmcnt(0)
	s_barrier
	s_cbranch_scc1 .LBB0_1888

.LBB0_1886:
	v_cndmask_b32_e64 v8, v48, v44, s[40:41]
	v_exp_f32_e32 v44, v116
	v_cndmask_b32_e64 v7, v51, v47, s[40:41]
	v_cndmask_b32_e64 v6, v50, v46, s[40:41]
	v_cndmask_b32_e64 v9, v49, v45, s[40:41]
	v_pk_add_f32 v[8:9], v[8:9], v[76:77]
	v_pk_add_f32 v[6:7], v[6:7], v[78:79]
	s_nop 0
	v_pk_fma_f32 v[2:3], v[44:45], v[8:9], v[2:3] op_sel_hi:[0,1,1]
	v_pk_fma_f32 v[4:5], v[44:45], v[6:7], v[4:5] op_sel_hi:[0,1,1]
	v_lshl_add_u32 v10, v10, 12, s1
	v_cvt_pk_bf16_f32 v2, v2, v3
	v_cvt_pk_bf16_f32 v3, v4, v5
	v_lshl_add_u64 v[4:5], v[10:11], 1, v[92:93]
	global_store_dwordx2 v[4:5], v[2:3], off
	v_mov_b32_e32 v2, s65
	ds_read_b32 v10, v2 offset:508
	s_sub_i32 s52, 0x26800, s65
	v_add_u32_e32 v192, s52, v182
	ds_read_b128 v[228:231], v192
	ds_read_b128 v[232:235], v192 offset:64
	ds_read_b128 v[236:239], v192 offset:128
	ds_read_b128 v[240:243], v192 offset:192
	ds_read_b128 v[244:247], v192 offset:256
	ds_read_b128 v[212:215], v192 offset:320
	ds_read_b128 v[216:219], v192 offset:384
	ds_read_b128 v[196:199], v192 offset:448
	v_lshlrev_b32_e32 v4, 16, v24
	v_and_b32_e32 v5, 0xffff0000, v24
	v_lshlrev_b32_e32 v6, 16, v25
	v_and_b32_e32 v7, 0xffff0000, v25
	s_waitcnt lgkmcnt(0)
	v_lshlrev_b32_e32 v8, 16, v27
	v_and_b32_e32 v9, 0xffff0000, v27
	v_lshlrev_b32_e32 v44, 16, v12
	v_pk_mul_f32 v[2:3], v[228:229], v[4:5]
	v_and_b32_e32 v45, 0xffff0000, v12
	v_cvt_pk_bf16_f32 v2, v2, v3
	s_nor_b64 s[2:3], s[36:37], s[30:31]
	v_pk_mul_f32 v[4:5], v[230:231], v[6:7]
	s_nop 0
	v_cvt_pk_bf16_f32 v3, v4, v5
	v_lshlrev_b32_e32 v6, 16, v26
	v_and_b32_e32 v7, 0xffff0000, v26
	v_pk_mul_f32 v[4:5], v[232:233], v[6:7]
	s_nop 0
	v_cvt_pk_bf16_f32 v4, v4, v5
	s_nop 0
	v_pk_mul_f32 v[6:7], v[234:235], v[8:9]
	s_nop 0
	v_cvt_pk_bf16_f32 v5, v6, v7
	v_lshlrev_b32_e32 v8, 16, v20
	v_and_b32_e32 v9, 0xffff0000, v20
	v_lshlrev_b32_e32 v20, 16, v21
	v_pk_mul_f32 v[6:7], v[236:237], v[8:9]
	v_and_b32_e32 v21, 0xffff0000, v21
	v_cvt_pk_bf16_f32 v6, v6, v7
	s_nop 0
	v_pk_mul_f32 v[8:9], v[238:239], v[20:21]
	s_nop 0
	v_cvt_pk_bf16_f32 v7, v8, v9
	v_lshlrev_b32_e32 v20, 16, v22
	v_and_b32_e32 v21, 0xffff0000, v22
	v_lshlrev_b32_e32 v22, 16, v23
	v_pk_mul_f32 v[8:9], v[240:241], v[20:21]
	v_and_b32_e32 v23, 0xffff0000, v23
	v_cvt_pk_bf16_f32 v8, v8, v9
	s_nop 0
	v_pk_mul_f32 v[20:21], v[242:243], v[22:23]
	s_nop 0
	v_cvt_pk_bf16_f32 v9, v20, v21
	v_lshlrev_b32_e32 v22, 16, v16
	v_and_b32_e32 v23, 0xffff0000, v16
	v_pk_mul_f32 v[20:21], v[244:245], v[22:23]
	s_nop 0
	v_cvt_pk_bf16_f32 v16, v20, v21
	v_lshlrev_b32_e32 v22, 16, v17
	v_and_b32_e32 v23, 0xffff0000, v17
	v_pk_mul_f32 v[20:21], v[246:247], v[22:23]
	s_nop 0
	v_cvt_pk_bf16_f32 v17, v20, v21
	v_lshlrev_b32_e32 v22, 16, v18
	v_and_b32_e32 v23, 0xffff0000, v18
	v_add_u32_e32 v52, v114, v174
	v_pk_mul_f32 v[20:21], v[212:213], v[22:23]
	v_lshlrev_b32_e32 v22, 16, v19
	v_cvt_pk_bf16_f32 v18, v20, v21
	v_and_b32_e32 v23, 0xffff0000, v19
	v_add_u32_e32 v48, 0x8800, v52
	v_pk_mul_f32 v[20:21], v[214:215], v[22:23]
	s_nop 0
	v_cvt_pk_bf16_f32 v19, v20, v21
	s_waitcnt lgkmcnt(0)
	s_nop 0
	v_pk_mul_f32 v[20:21], v[216:217], v[44:45]
	s_nop 0
	v_cvt_pk_bf16_f32 v12, v20, v21
	v_lshlrev_b32_e32 v22, 16, v13
	v_and_b32_e32 v23, 0xffff0000, v13
	v_pk_mul_f32 v[20:21], v[218:219], v[22:23]
	s_nop 0
	v_cvt_pk_bf16_f32 v13, v20, v21
	v_lshlrev_b32_e32 v22, 16, v14
	v_and_b32_e32 v23, 0xffff0000, v14
	v_pk_mul_f32 v[20:21], v[196:197], v[22:23]
	s_nop 0
	v_cvt_pk_bf16_f32 v14, v20, v21
	v_exp_f32_e32 v10, v181
	v_lshlrev_b32_e32 v22, 16, v15
	v_and_b32_e32 v23, 0xffff0000, v15
	v_pk_mul_f32 v[20:21], v[198:199], v[22:23]
	v_pk_mul_f32 v[30:31], v[30:31], v[10:11] op_sel_hi:[1,0]
	v_cvt_pk_bf16_f32 v15, v20, v21
	ds_read2_b64 v[20:23], v48 offset1:4
	ds_read2_b64 v[24:27], v48 offset0:8 offset1:12
	ds_read2_b64 v[44:47], v48 offset0:16 offset1:20
	ds_read2_b64 v[48:51], v48 offset0:24 offset1:28
	v_pk_mul_f32 v[28:29], v[28:29], v[10:11] op_sel_hi:[1,0]
	v_pk_mul_f32 v[34:35], v[34:35], v[10:11] op_sel_hi:[1,0]
	v_pk_mul_f32 v[32:33], v[32:33], v[10:11] op_sel_hi:[1,0]
	s_waitcnt lgkmcnt(0)
	v_mfma_f32_16x16x32_bf16 v[20:23], v[20:23], v[2:5], v[28:31]
	v_mul_f32_e64 v38, v38, v10
	v_mul_f32_e64 v39, v39, v10
	v_pk_mul_f32 v[36:37], v[36:37], v[10:11] op_sel_hi:[1,0]
	v_pk_mul_f32 v[42:43], v[42:43], v[10:11] op_sel_hi:[1,0]
	v_mfma_f32_16x16x32_bf16 v[20:23], v[24:27], v[6:9], v[20:23]
	v_mul_f32_e64 v40, v40, v10
	v_mul_f32_e64 v41, v41, v10
	v_mfma_f32_16x16x32_bf16 v[20:23], v[44:47], v[16:19], v[20:23]
	v_mfma_f32_16x16x32_bf16 v[28:31], v[48:51], v[12:15], v[20:23]
	v_add_u32_e32 v48, 0x9800, v52
	s_nop 5
	ds_read2_b64 v[20:23], v48 offset0:32 offset1:36
	ds_read2_b64 v[24:27], v48 offset0:40 offset1:44
	ds_read2_b64 v[44:47], v48 offset0:48 offset1:52
	ds_read2_b64 v[48:51], v48 offset0:56 offset1:60
	s_waitcnt lgkmcnt(0)
	v_mfma_f32_16x16x32_bf16 v[20:23], v[20:23], v[2:5], v[32:35]
	v_mfma_f32_16x16x32_bf16 v[20:23], v[24:27], v[6:9], v[20:23]
	v_mfma_f32_16x16x32_bf16 v[20:23], v[44:47], v[16:19], v[20:23]
	v_mfma_f32_16x16x32_bf16 v[32:35], v[48:51], v[12:15], v[20:23]
	v_add_u32_e32 v48, 0xa800, v52
	s_nop 5
	ds_read2_b64 v[20:23], v48 offset0:64 offset1:68
	ds_read2_b64 v[24:27], v48 offset0:72 offset1:76
	ds_read2_b64 v[44:47], v48 offset0:80 offset1:84
	ds_read2_b64 v[48:51], v48 offset0:88 offset1:92
	s_waitcnt lgkmcnt(0)
	v_mfma_f32_16x16x32_bf16 v[20:23], v[20:23], v[2:5], v[36:39]
	v_mfma_f32_16x16x32_bf16 v[20:23], v[24:27], v[6:9], v[20:23]
	v_mfma_f32_16x16x32_bf16 v[20:23], v[44:47], v[16:19], v[20:23]
	v_mfma_f32_16x16x32_bf16 v[36:39], v[48:51], v[12:15], v[20:23]
	s_nop 6
	v_add_u32_e32 v20, v114, v175
	v_add_u32_e32 v48, 0x8800, v20
	ds_read2_b64 v[20:23], v48 offset1:4
	ds_read2_b64 v[24:27], v48 offset0:8 offset1:12
	ds_read2_b64 v[44:47], v48 offset0:16 offset1:20
	ds_read2_b64 v[48:51], v48 offset0:24 offset1:28
	s_waitcnt lgkmcnt(0)
	v_mfma_f32_16x16x32_bf16 v[2:5], v[20:23], v[2:5], v[40:43]
	v_mfma_f32_16x16x32_bf16 v[2:5], v[24:27], v[6:9], v[2:5]
	v_mfma_f32_16x16x32_bf16 v[2:5], v[44:47], v[16:19], v[2:5]
	v_mfma_f32_16x16x32_bf16 v[40:43], v[48:51], v[12:15], v[2:5]
	s_and_saveexec_b64 s[30:31], s[2:3]
	s_cbranch_execz .LBB0_1649
	s_xor_b32 s2, s5, 0x400
	s_waitcnt vmcnt(2)
	s_nop 2
	v_mul_f32_e32 v2, 0x3fb8aa3b, v89
	v_add_u32_e32 v3, s2, v180
	ds_write2st64_b32 v3, v2, v95 offset1:2
	s_branch .LBB0_1649
